# grid barrier: first local arriver of each XCD issues an early async L2 writeback so the leader's release flush finds few dirty lines
# speedup vs baseline: 1.0159x; 1.0159x over previous
; __device__ __forceinline__ unsigned xb_ld(unsigned* p)              { return __hip_atomic_load(p, __ATOMIC_RELAXED, __HIP_MEMORY_SCOPE_AGENT); }
; __device__ __forceinline__ unsigned xb_add(unsigned* p, unsigned v) { return __hip_atomic_fetch_add(p, v, __ATOMIC_RELAXED, __HIP_MEMORY_SCOPE_AGENT); }
; #define XB_SPIN(cond, bar) do { unsigned _sp = 0; while (cond) { __builtin_amdgcn_s_sleep(1); \
;     if ((++_sp & 255u) == 0u) { if (xb_ld(&(bar)[XB_TMO])) break; if (_sp > XB_SPIN_CAP) { atomicAdd(&(bar)[XB_TMO], 1u); break; } } } } while (0)
; __device__ __forceinline__ void xcd_barrier(const XcdBarrier& b) {
;     ...
;         const unsigned old = xb_add(&bar[XB_XSUB(b.x)], 1u);
;         const unsigned gen = old / nloc;
;         if (old + 1u == (gen + 1u) * nloc) {
;             __builtin_amdgcn_fence(__ATOMIC_RELEASE, "agent");
;             asm volatile("s_waitcnt vmcnt(0)" ::: "memory");
;             const unsigned og = xb_add(&bar[XB_TOP], 1u);
;             const unsigned tg = og / nx;
;             if (og + 1u == (tg + 1u) * nx) xb_add(&bar[XB_TOPGEN], 1u);
;             else XB_SPIN(xb_ld(&bar[XB_TOPGEN]) == tg, bar);
;             __builtin_amdgcn_fence(__ATOMIC_ACQUIRE, "agent");
;             xb_add(&bar[XB_XGEN(b.x)], 1u);
;             asm volatile("s_waitcnt vmcnt(0)" ::: "memory");
;         } else {
;             XB_SPIN(xb_ld(&bar[XB_XGEN(b.x)]) == gen, bar);
.LBB0_54:
	s_or_b64 exec, exec, s[12:13]
	v_cvt_f32_u32_e32 v5, v3
	s_waitcnt vmcnt(0)
	v_readfirstlane_b32 s0, v4
	v_sub_u32_e32 v4, 0, v3
	v_rcp_iflag_f32_e32 v5, v5
	v_add_u32_e32 v6, s0, v2
	v_mul_f32_e32 v5, 0x4f7ffffe, v5
	v_cvt_u32_f32_e32 v5, v5
	v_mul_lo_u32 v2, v4, v5
	v_mul_hi_u32 v2, v5, v2
	v_add_u32_e32 v2, v5, v2
	v_mul_hi_u32 v2, v6, v2
	v_mul_lo_u32 v4, v2, v3
	v_sub_u32_e32 v4, v6, v4
	v_add_u32_e32 v5, 1, v2
	v_cmp_ge_u32_e32 vcc, v4, v3
	s_nop 1
	v_cndmask_b32_e32 v2, v2, v5, vcc
	v_sub_u32_e32 v5, v4, v3
	v_cndmask_b32_e32 v4, v4, v5, vcc
	v_add_u32_e32 v5, 1, v2
	v_cmp_ge_u32_e32 vcc, v4, v3
	v_add_u32_e32 v4, 1, v6
	s_nop 0
	v_cndmask_b32_e32 v2, v2, v5, vcc
	v_mul_lo_u32 v5, v3, v2
	v_add_u32_e32 v3, v5, v3
	v_cmp_ne_u32_e32 vcc, v4, v3
	s_and_saveexec_b64 s[0:1], vcc
	s_xor_b64 s[10:11], exec, s[0:1]
	s_cbranch_execz .LBB0_68
	v_readfirstlane_b32 s98, v4
	v_readfirstlane_b32 s99, v5
	s_add_i32 s99, s99, 1
	s_cmp_eq_u32 s98, s99
	s_cbranch_scc0 .Lxb_nf_9
	buffer_wbl2 sc1
.Lxb_nf_9:
	s_waitcnt lgkmcnt(0)
	v_mov_b32_e32 v1, 0x2000
	global_load_dword v1, v1, s[8:9] offset:1024 sc1
	s_add_u32 s18, s8, 0x2400
	s_addc_u32 s19, s9, 0
	s_waitcnt vmcnt(0)
	v_cmp_eq_u32_e32 vcc, v1, v2
	s_and_saveexec_b64 s[12:13], vcc
	s_cbranch_execz .LBB0_67
	s_add_u32 s14, s6, 0x80200
	s_addc_u32 s15, s7, 0
	s_mov_b32 s0, 1
	s_mov_b64 s[20:21], 0
	v_mov_b32_e32 v1, 0
	s_branch .LBB0_58

; __device__ __forceinline__ unsigned xb_ld(unsigned* p)              { return __hip_atomic_load(p, __ATOMIC_RELAXED, __HIP_MEMORY_SCOPE_AGENT); }
; __device__ __forceinline__ unsigned xb_add(unsigned* p, unsigned v) { return __hip_atomic_fetch_add(p, v, __ATOMIC_RELAXED, __HIP_MEMORY_SCOPE_AGENT); }
; #define XB_SPIN(cond, bar) do { unsigned _sp = 0; while (cond) { __builtin_amdgcn_s_sleep(1); \
;     if ((++_sp & 255u) == 0u) { if (xb_ld(&(bar)[XB_TMO])) break; if (_sp > XB_SPIN_CAP) { atomicAdd(&(bar)[XB_TMO], 1u); break; } } } } while (0)
; __device__ __forceinline__ void xcd_barrier(const XcdBarrier& b) {
;     ...
;         const unsigned old = xb_add(&bar[XB_XSUB(b.x)], 1u);
;         const unsigned gen = old / nloc;
;         if (old + 1u == (gen + 1u) * nloc) {
;             __builtin_amdgcn_fence(__ATOMIC_RELEASE, "agent");
;             asm volatile("s_waitcnt vmcnt(0)" ::: "memory");
;             const unsigned og = xb_add(&bar[XB_TOP], 1u);
;             const unsigned tg = og / nx;
;             if (og + 1u == (tg + 1u) * nx) xb_add(&bar[XB_TOPGEN], 1u);
;             else XB_SPIN(xb_ld(&bar[XB_TOPGEN]) == tg, bar);
;             __builtin_amdgcn_fence(__ATOMIC_ACQUIRE, "agent");
;             xb_add(&bar[XB_XGEN(b.x)], 1u);
;             asm volatile("s_waitcnt vmcnt(0)" ::: "memory");
;         } else {
;             XB_SPIN(xb_ld(&bar[XB_XGEN(b.x)]) == gen, bar);
.LBB0_125:
	s_or_b64 exec, exec, s[12:13]
	v_cvt_f32_u32_e32 v4, v2
	s_waitcnt vmcnt(0)
	v_readfirstlane_b32 s0, v3
	v_sub_u32_e32 v3, 0, v2
	v_rcp_iflag_f32_e32 v4, v4
	v_add_u32_e32 v5, s0, v1
	v_mul_f32_e32 v4, 0x4f7ffffe, v4
	v_cvt_u32_f32_e32 v4, v4
	v_mul_lo_u32 v1, v3, v4
	v_mul_hi_u32 v1, v4, v1
	v_add_u32_e32 v1, v4, v1
	v_mul_hi_u32 v1, v5, v1
	v_mul_lo_u32 v3, v1, v2
	v_sub_u32_e32 v3, v5, v3
	v_add_u32_e32 v4, 1, v1
	v_cmp_ge_u32_e32 vcc, v3, v2
	s_nop 1
	v_cndmask_b32_e32 v1, v1, v4, vcc
	v_sub_u32_e32 v4, v3, v2
	v_cndmask_b32_e32 v3, v3, v4, vcc
	v_add_u32_e32 v4, 1, v1
	v_cmp_ge_u32_e32 vcc, v3, v2
	v_add_u32_e32 v3, 1, v5
	s_nop 0
	v_cndmask_b32_e32 v1, v1, v4, vcc
	v_mul_lo_u32 v4, v2, v1
	v_add_u32_e32 v2, v4, v2
	v_cmp_ne_u32_e32 vcc, v3, v2
	s_and_saveexec_b64 s[0:1], vcc
	s_xor_b64 s[10:11], exec, s[0:1]
	s_cbranch_execz .LBB0_139
	v_readfirstlane_b32 s98, v3
	v_readfirstlane_b32 s99, v4
	s_add_i32 s99, s99, 1
	s_cmp_eq_u32 s98, s99
	s_cbranch_scc0 .Lxb_nf_8
	buffer_wbl2 sc1
.Lxb_nf_8:
	s_waitcnt lgkmcnt(0)
	v_mov_b32_e32 v0, 0x2000
	global_load_dword v0, v0, s[8:9] offset:1024 sc1
	s_add_u32 s16, s8, 0x2400
	s_addc_u32 s17, s9, 0
	s_waitcnt vmcnt(0)
	v_cmp_eq_u32_e32 vcc, v0, v1
	s_and_saveexec_b64 s[12:13], vcc
	s_cbranch_execz .LBB0_138
	s_add_u32 s14, s6, 0x80200
	s_addc_u32 s15, s7, 0
	s_mov_b32 s0, 1
	s_mov_b64 s[18:19], 0
	v_mov_b32_e32 v0, 0
	s_branch .LBB0_129

; __device__ __forceinline__ unsigned xb_ld(unsigned* p)              { return __hip_atomic_load(p, __ATOMIC_RELAXED, __HIP_MEMORY_SCOPE_AGENT); }
; __device__ __forceinline__ unsigned xb_add(unsigned* p, unsigned v) { return __hip_atomic_fetch_add(p, v, __ATOMIC_RELAXED, __HIP_MEMORY_SCOPE_AGENT); }
; #define XB_SPIN(cond, bar) do { unsigned _sp = 0; while (cond) { __builtin_amdgcn_s_sleep(1); \
;     if ((++_sp & 255u) == 0u) { if (xb_ld(&(bar)[XB_TMO])) break; if (_sp > XB_SPIN_CAP) { atomicAdd(&(bar)[XB_TMO], 1u); break; } } } } while (0)
; __device__ __forceinline__ void xcd_barrier(const XcdBarrier& b) {
;     ...
;         const unsigned old = xb_add(&bar[XB_XSUB(b.x)], 1u);
;         const unsigned gen = old / nloc;
;         if (old + 1u == (gen + 1u) * nloc) {
;             __builtin_amdgcn_fence(__ATOMIC_RELEASE, "agent");
;             asm volatile("s_waitcnt vmcnt(0)" ::: "memory");
;             const unsigned og = xb_add(&bar[XB_TOP], 1u);
;             const unsigned tg = og / nx;
;             if (og + 1u == (tg + 1u) * nx) xb_add(&bar[XB_TOPGEN], 1u);
;             else XB_SPIN(xb_ld(&bar[XB_TOPGEN]) == tg, bar);
;             __builtin_amdgcn_fence(__ATOMIC_ACQUIRE, "agent");
;             xb_add(&bar[XB_XGEN(b.x)], 1u);
;             asm volatile("s_waitcnt vmcnt(0)" ::: "memory");
;         } else {
;             XB_SPIN(xb_ld(&bar[XB_XGEN(b.x)]) == gen, bar);
.LBB0_566:
	s_or_b64 exec, exec, s[18:19]
	v_cvt_f32_u32_e32 v4, v2
	s_waitcnt vmcnt(0)
	v_readfirstlane_b32 s0, v3
	v_sub_u32_e32 v3, 0, v2
	v_rcp_iflag_f32_e32 v4, v4
	v_add_u32_e32 v5, s0, v1
	v_mul_f32_e32 v4, 0x4f7ffffe, v4
	v_cvt_u32_f32_e32 v4, v4
	v_mul_lo_u32 v1, v3, v4
	v_mul_hi_u32 v1, v4, v1
	v_add_u32_e32 v1, v4, v1
	v_mul_hi_u32 v1, v5, v1
	v_mul_lo_u32 v3, v1, v2
	v_sub_u32_e32 v3, v5, v3
	v_add_u32_e32 v4, 1, v1
	v_cmp_ge_u32_e32 vcc, v3, v2
	s_nop 1
	v_cndmask_b32_e32 v1, v1, v4, vcc
	v_sub_u32_e32 v4, v3, v2
	v_cndmask_b32_e32 v3, v3, v4, vcc
	v_add_u32_e32 v4, 1, v1
	v_cmp_ge_u32_e32 vcc, v3, v2
	v_add_u32_e32 v3, 1, v5
	s_nop 0
	v_cndmask_b32_e32 v1, v1, v4, vcc
	v_mul_lo_u32 v4, v2, v1
	v_add_u32_e32 v2, v4, v2
	v_cmp_ne_u32_e32 vcc, v3, v2
	s_and_saveexec_b64 s[0:1], vcc
	s_xor_b64 s[16:17], exec, s[0:1]
	s_cbranch_execz .LBB0_580
	v_readfirstlane_b32 s98, v3
	v_readfirstlane_b32 s99, v4
	s_add_i32 s99, s99, 1
	s_cmp_eq_u32 s98, s99
	s_cbranch_scc0 .Lxb_nf_5
	buffer_wbl2 sc1
.Lxb_nf_5:
	s_waitcnt lgkmcnt(0)
	v_mov_b32_e32 v0, 0x2000
	global_load_dword v0, v0, s[10:11] offset:1024 sc1
	s_add_u32 s22, s10, 0x2400
	s_addc_u32 s23, s11, 0
	s_waitcnt vmcnt(0)
	v_cmp_eq_u32_e32 vcc, v0, v1
	s_and_saveexec_b64 s[18:19], vcc
	s_cbranch_execz .LBB0_579
	s_add_u32 s20, s8, 0x80200
	s_addc_u32 s21, s9, 0
	s_mov_b32 s0, 1
	s_mov_b64 s[24:25], 0
	v_mov_b32_e32 v0, 0
	s_branch .LBB0_570

; __device__ __forceinline__ unsigned xb_ld(unsigned* p)              { return __hip_atomic_load(p, __ATOMIC_RELAXED, __HIP_MEMORY_SCOPE_AGENT); }
; __device__ __forceinline__ unsigned xb_add(unsigned* p, unsigned v) { return __hip_atomic_fetch_add(p, v, __ATOMIC_RELAXED, __HIP_MEMORY_SCOPE_AGENT); }
; #define XB_SPIN(cond, bar) do { unsigned _sp = 0; while (cond) { __builtin_amdgcn_s_sleep(1); \
;     if ((++_sp & 255u) == 0u) { if (xb_ld(&(bar)[XB_TMO])) break; if (_sp > XB_SPIN_CAP) { atomicAdd(&(bar)[XB_TMO], 1u); break; } } } } while (0)
; __device__ __forceinline__ void xcd_barrier(const XcdBarrier& b) {
;     ...
;         const unsigned old = xb_add(&bar[XB_XSUB(b.x)], 1u);
;         const unsigned gen = old / nloc;
;         if (old + 1u == (gen + 1u) * nloc) {
;             __builtin_amdgcn_fence(__ATOMIC_RELEASE, "agent");
;             asm volatile("s_waitcnt vmcnt(0)" ::: "memory");
;             const unsigned og = xb_add(&bar[XB_TOP], 1u);
;             const unsigned tg = og / nx;
;             if (og + 1u == (tg + 1u) * nx) xb_add(&bar[XB_TOPGEN], 1u);
;             else XB_SPIN(xb_ld(&bar[XB_TOPGEN]) == tg, bar);
;             __builtin_amdgcn_fence(__ATOMIC_ACQUIRE, "agent");
;             xb_add(&bar[XB_XGEN(b.x)], 1u);
;             asm volatile("s_waitcnt vmcnt(0)" ::: "memory");
;         } else {
;             XB_SPIN(xb_ld(&bar[XB_XGEN(b.x)]) == gen, bar);
.LBB0_638:
	s_or_b64 exec, exec, s[16:17]
	v_cvt_f32_u32_e32 v4, v2
	s_waitcnt vmcnt(0)
	v_readfirstlane_b32 s0, v3
	v_sub_u32_e32 v3, 0, v2
	v_rcp_iflag_f32_e32 v4, v4
	v_add_u32_e32 v5, s0, v1
	v_mul_f32_e32 v4, 0x4f7ffffe, v4
	v_cvt_u32_f32_e32 v4, v4
	v_mul_lo_u32 v1, v3, v4
	v_mul_hi_u32 v1, v4, v1
	v_add_u32_e32 v1, v4, v1
	v_mul_hi_u32 v1, v5, v1
	v_mul_lo_u32 v3, v1, v2
	v_sub_u32_e32 v3, v5, v3
	v_add_u32_e32 v4, 1, v1
	v_cmp_ge_u32_e32 vcc, v3, v2
	s_nop 1
	v_cndmask_b32_e32 v1, v1, v4, vcc
	v_sub_u32_e32 v4, v3, v2
	v_cndmask_b32_e32 v3, v3, v4, vcc
	v_add_u32_e32 v4, 1, v1
	v_cmp_ge_u32_e32 vcc, v3, v2
	v_add_u32_e32 v3, 1, v5
	s_nop 0
	v_cndmask_b32_e32 v1, v1, v4, vcc
	v_mul_lo_u32 v4, v2, v1
	v_add_u32_e32 v2, v4, v2
	v_cmp_ne_u32_e32 vcc, v3, v2
	s_and_saveexec_b64 s[0:1], vcc
	s_xor_b64 s[10:11], exec, s[0:1]
	s_cbranch_execz .LBB0_652
	v_readfirstlane_b32 s98, v3
	v_readfirstlane_b32 s99, v4
	s_add_i32 s99, s99, 1
	s_cmp_eq_u32 s98, s99
	s_cbranch_scc0 .Lxb_nf_4
	buffer_wbl2 sc1
.Lxb_nf_4:
	s_waitcnt lgkmcnt(0)
	v_mov_b32_e32 v0, 0x2000
	global_load_dword v0, v0, s[8:9] offset:1024 sc1
	s_add_u32 s20, s8, 0x2400
	s_addc_u32 s21, s9, 0
	s_waitcnt vmcnt(0)
	v_cmp_eq_u32_e32 vcc, v0, v1
	s_and_saveexec_b64 s[16:17], vcc
	s_cbranch_execz .LBB0_651
	s_add_u32 s18, s6, 0x80200
	s_addc_u32 s19, s7, 0
	s_mov_b32 s0, 1
	s_mov_b64 s[22:23], 0
	v_mov_b32_e32 v0, 0
	s_branch .LBB0_642

; __device__ __forceinline__ unsigned xb_ld(unsigned* p)              { return __hip_atomic_load(p, __ATOMIC_RELAXED, __HIP_MEMORY_SCOPE_AGENT); }
; __device__ __forceinline__ unsigned xb_add(unsigned* p, unsigned v) { return __hip_atomic_fetch_add(p, v, __ATOMIC_RELAXED, __HIP_MEMORY_SCOPE_AGENT); }
; #define XB_SPIN(cond, bar) do { unsigned _sp = 0; while (cond) { __builtin_amdgcn_s_sleep(1); \
;     if ((++_sp & 255u) == 0u) { if (xb_ld(&(bar)[XB_TMO])) break; if (_sp > XB_SPIN_CAP) { atomicAdd(&(bar)[XB_TMO], 1u); break; } } } } while (0)
; __device__ __forceinline__ void xcd_barrier(const XcdBarrier& b) {
;     ...
;         const unsigned old = xb_add(&bar[XB_XSUB(b.x)], 1u);
;         const unsigned gen = old / nloc;
;         if (old + 1u == (gen + 1u) * nloc) {
;             __builtin_amdgcn_fence(__ATOMIC_RELEASE, "agent");
;             asm volatile("s_waitcnt vmcnt(0)" ::: "memory");
;             const unsigned og = xb_add(&bar[XB_TOP], 1u);
;             const unsigned tg = og / nx;
;             if (og + 1u == (tg + 1u) * nx) xb_add(&bar[XB_TOPGEN], 1u);
;             else XB_SPIN(xb_ld(&bar[XB_TOPGEN]) == tg, bar);
;             __builtin_amdgcn_fence(__ATOMIC_ACQUIRE, "agent");
;             xb_add(&bar[XB_XGEN(b.x)], 1u);
;             asm volatile("s_waitcnt vmcnt(0)" ::: "memory");
;         } else {
;             XB_SPIN(xb_ld(&bar[XB_XGEN(b.x)]) == gen, bar);
.LBB0_919:
	s_or_b64 exec, exec, s[10:11]
	v_cvt_f32_u32_e32 v4, v2
	s_waitcnt vmcnt(0)
	v_readfirstlane_b32 s0, v3
	v_sub_u32_e32 v3, 0, v2
	v_rcp_iflag_f32_e32 v4, v4
	v_add_u32_e32 v5, s0, v1
	v_mul_f32_e32 v4, 0x4f7ffffe, v4
	v_cvt_u32_f32_e32 v4, v4
	v_mul_lo_u32 v1, v3, v4
	v_mul_hi_u32 v1, v4, v1
	v_add_u32_e32 v1, v4, v1
	v_mul_hi_u32 v1, v5, v1
	v_mul_lo_u32 v3, v1, v2
	v_sub_u32_e32 v3, v5, v3
	v_add_u32_e32 v4, 1, v1
	v_cmp_ge_u32_e32 vcc, v3, v2
	s_nop 1
	v_cndmask_b32_e32 v1, v1, v4, vcc
	v_sub_u32_e32 v4, v3, v2
	v_cndmask_b32_e32 v3, v3, v4, vcc
	v_add_u32_e32 v4, 1, v1
	v_cmp_ge_u32_e32 vcc, v3, v2
	v_add_u32_e32 v3, 1, v5
	s_nop 0
	v_cndmask_b32_e32 v1, v1, v4, vcc
	v_mul_lo_u32 v4, v2, v1
	v_add_u32_e32 v2, v4, v2
	v_cmp_ne_u32_e32 vcc, v3, v2
	s_and_saveexec_b64 s[0:1], vcc
	s_xor_b64 s[8:9], exec, s[0:1]
	s_cbranch_execz .LBB0_933
	v_readfirstlane_b32 s98, v3
	v_readfirstlane_b32 s99, v4
	s_add_i32 s99, s99, 1
	s_cmp_eq_u32 s98, s99
	s_cbranch_scc0 .Lxb_nf_0
	buffer_wbl2 sc1
.Lxb_nf_0:
	s_waitcnt lgkmcnt(0)
	v_mov_b32_e32 v0, 0x2000
	global_load_dword v0, v0, s[6:7] offset:1024 sc1
	s_add_u32 s14, s6, 0x2400
	s_addc_u32 s15, s7, 0
	s_waitcnt vmcnt(0)
	v_cmp_eq_u32_e32 vcc, v0, v1
	s_and_saveexec_b64 s[10:11], vcc
	s_cbranch_execz .LBB0_932
	s_add_u32 s12, s4, 0x80200
	s_addc_u32 s13, s5, 0
	s_mov_b32 s0, 1
	s_mov_b64 s[16:17], 0
	v_mov_b32_e32 v0, 0
	s_branch .LBB0_923
